# v61 + MLA loop heads: pre-MFMA VALU interleaved between the five DMA issues of the next-tile block
# speedup vs baseline: 1.0147x; 1.0038x over previous
.Lmla_nopf_valu:
	v_fmamk_f32 v224, v82, 0x3dd53b94, v154
	v_fmamk_f32 v225, v83, 0x3dd53b94, v154
	v_fmamk_f32 v226, v84, 0x3dd53b94, v154
	v_fmamk_f32 v227, v85, 0x3dd53b94, v154
	v_fmamk_f32 v228, v86, 0x3dd53b94, v154
	v_fmamk_f32 v229, v87, 0x3dd53b94, v154
	v_fmamk_f32 v230, v88, 0x3dd53b94, v154
	v_fmamk_f32 v231, v89, 0x3dd53b94, v154
	v_fmamk_f32 v234, v90, 0x3dd53b94, v154
	v_fmamk_f32 v235, v91, 0x3dd53b94, v154
	v_fmamk_f32 v236, v92, 0x3dd53b94, v154
	v_fmamk_f32 v237, v93, 0x3dd53b94, v154
	v_fmamk_f32 v238, v94, 0x3dd53b94, v154
	v_fmamk_f32 v239, v95, 0x3dd53b94, v154
	v_fmamk_f32 v240, v96, 0x3dd53b94, v154
	v_fmamk_f32 v241, v97, 0x3dd53b94, v154
	s_branch .Lattn_mla_nopf
.LBB0_543:
	s_mov_b32 s23, s17
	s_mov_b32 s17, s0
	s_add_i32 s71, 0, 0x10000
	ds_read_b128 v[66:69], v174 offset:49152
	ds_read_b128 v[70:73], v174 offset:57344
	ds_read_b128 v[206:209], v176 offset:49152
	ds_read_b128 v[210:213], v176 offset:57344
	s_add_u32 s4, s38, s20
	s_addc_u32 s5, s39, s21
	s_add_u32 s24, s4, 0x149ec400
	s_addc_u32 s25, s5, 0
	s_mov_b32 m0, s90
	s_lshl_b32 s18, s22, 14
	global_load_lds_dwordx4 v246, s[24:25]
	v_fma_f32 v152, v74, s34, v146
	v_fma_f32 v153, v75, s34, v146
	v_fma_f32 v150, v76, s34, v146
	s_add_u32 s24, s4, 0x14a0c400
	s_addc_u32 s25, s5, 0
	s_mov_b32 m0, s91
	s_add_i32 s1, s89, s18
	global_load_lds_dwordx4 v246, s[24:25]
	v_fma_f32 v151, v77, s34, v146
	v_fma_f32 v148, v78, s34, v146
	v_fma_f32 v149, v79, s34, v146
	s_add_u32 s24, s4, 0x149ec500
	s_addc_u32 s25, s5, 0
	s_mov_b32 m0, s1
	s_nop 0
	global_load_lds_dwordx4 v248, s[24:25]
	v_fma_f32 v147, v81, s34, v146
	v_fma_f32 v146, v80, s34, v146
	v_exp_f32_e32 v229, v229
	s_add_u32 s24, s4, 0x14a0c500
	s_addc_u32 s25, s5, 0
	s_add_i32 m0, s1, 0x2000
	s_nop 0
	global_load_lds_dwordx4 v248, s[24:25]
	v_exp_f32_e32 v231, v231
	v_exp_f32_e32 v227, v227
	v_exp_f32_e32 v230, v230
	s_add_u32 s4, s38, s88
	s_addc_u32 s5, s39, s87
	s_add_u32 s4, s4, s36
	s_addc_u32 s5, s5, s37
	s_mov_b32 m0, s92
	s_nop 0
	global_load_lds_dwordx4 v250, s[4:5]
	v_exp_f32_e32 v226, v226
	v_exp_f32_e32 v228, v228
	s_waitcnt lgkmcnt(0)
	v_mfma_f32_32x32x16_bf16 v[82:97], v[66:69], v[142:145], 0
	s_add_i32 s0, 0, 0x16000
	v_exp_f32_e32 v240, v146
	v_add_f32_e32 v146, 0, v229
	v_add_f32_e32 v146, v231, v146
	v_add_f32_e32 v146, v227, v146
	v_add_f32_e32 v146, v230, v146
	v_add_f32_e32 v146, v226, v146
	v_exp_f32_e32 v224, v224
	v_exp_f32_e32 v225, v225
	v_exp_f32_e32 v221, v221
	v_exp_f32_e32 v223, v223
	v_mfma_f32_32x32x16_bf16 v[66:81], v[70:73], v[142:145], 0
	v_exp_f32_e32 v220, v220
	v_exp_f32_e32 v222, v222
	v_add_f32_e32 v146, v228, v146
	v_add_f32_e32 v146, v224, v146
	v_add_f32_e32 v146, v225, v146
	v_add_f32_e32 v146, v221, v146
	v_add_f32_e32 v146, v223, v146
	v_add_f32_e32 v146, v220, v146
	v_add_f32_e32 v146, v222, v146
	v_exp_f32_e32 v217, v217
	v_exp_f32_e32 v219, v219
	v_exp_f32_e32 v216, v216
	v_exp_f32_e32 v218, v218
	v_mfma_f32_32x32x16_bf16 v[82:97], v[206:209], v[138:141], v[82:97]
	v_exp_f32_e32 v164, v164
	v_add_f32_e32 v146, v217, v146
	v_exp_f32_e32 v165, v165
	v_add_f32_e32 v146, v219, v146
	v_exp_f32_e32 v197, v162
	v_add_f32_e32 v146, v216, v146
	v_add_f32_e32 v146, v218, v146
	v_mfma_f32_32x32x16_bf16 v[66:81], v[210:213], v[138:141], v[66:81]
	ds_read_b128 v[206:209], v178 offset:49152
	ds_read_b128 v[210:213], v178 offset:57344
	v_exp_f32_e32 v156, v156
	v_add_f32_e32 v146, v164, v146
	v_exp_f32_e32 v157, v157
	v_add_f32_e32 v146, v165, v146
	v_add_f32_e32 v146, v197, v146
	v_exp_f32_e32 v241, v147
	s_waitcnt lgkmcnt(0)
	v_mfma_f32_32x32x16_bf16 v[82:97], v[206:209], v[134:137], v[82:97]
	v_mfma_f32_32x32x16_bf16 v[66:81], v[210:213], v[134:137], v[66:81]
	ds_read_b128 v[208:211], v180 offset:49152
	ds_read_b128 v[212:215], v180 offset:57344
	s_waitcnt lgkmcnt(0)
	v_mfma_f32_32x32x16_bf16 v[82:97], v[208:211], v[130:133], v[82:97]
	v_mfma_f32_32x32x16_bf16 v[66:81], v[212:215], v[130:133], v[66:81]
	ds_read_b128 v[208:211], v182 offset:49152
	ds_read_b128 v[212:215], v182 offset:57344
	s_waitcnt lgkmcnt(0)
	v_mfma_f32_32x32x16_bf16 v[82:97], v[208:211], v[126:129], v[82:97]
	v_mfma_f32_32x32x16_bf16 v[66:81], v[212:215], v[126:129], v[66:81]
	ds_read_b128 v[210:213], v186 offset:49152
	ds_read_b128 v[232:235], v186 offset:57344
	s_waitcnt lgkmcnt(0)
	v_mfma_f32_32x32x16_bf16 v[82:97], v[210:213], v[122:125], v[82:97]
	v_mfma_f32_32x32x16_bf16 v[66:81], v[232:235], v[122:125], v[66:81]
	ds_read_b128 v[210:213], v188 offset:49152
	ds_read_b128 v[232:235], v188 offset:57344
	s_waitcnt lgkmcnt(0)
	v_mfma_f32_32x32x16_bf16 v[82:97], v[210:213], v[118:121], v[82:97]
	v_mfma_f32_32x32x16_bf16 v[66:81], v[232:235], v[118:121], v[66:81]
	ds_read_b128 v[212:215], v190 offset:49152
	ds_read_b128 v[232:235], v190 offset:57344
	s_waitcnt lgkmcnt(0)
	v_mfma_f32_32x32x16_bf16 v[82:97], v[212:215], v[114:117], v[82:97]
	v_mfma_f32_32x32x16_bf16 v[66:81], v[232:235], v[114:117], v[66:81]
	ds_read_b128 v[212:215], v192 offset:8192
	ds_read_b128 v[232:235], v192 offset:12288
	s_waitcnt lgkmcnt(0)
	v_mfma_f32_32x32x16_bf16 v[82:97], v[212:215], v[110:113], v[82:97]
	v_exp_f32_e32 v215, v163
	s_nop 0
	v_add_f32_e32 v146, v215, v146
	v_mfma_f32_32x32x16_bf16 v[66:81], v[232:235], v[110:113], v[66:81]
	s_lshl_b32 s24, s17, 14
	v_add_u32_e32 v245, s24, v200
	ds_read_b64_tr_b16 v[206:207], v245 offset:0
	ds_read_b64_tr_b16 v[208:209], v245 offset:0x800
	ds_read_b64_tr_b16 v[210:211], v245 offset:0x1000
	ds_read_b64_tr_b16 v[212:213], v245 offset:0x1800
	ds_read_b128 v[232:235], v194 offset:8192
	ds_read_b128 v[236:239], v194 offset:12288
	v_add_f32_e32 v146, v156, v146
	v_add_f32_e32 v146, v157, v146
	s_waitcnt lgkmcnt(0)
	v_mfma_f32_32x32x16_bf16 v[82:97], v[232:235], v[106:109], v[82:97]
	v_mfma_f32_32x32x16_bf16 v[66:81], v[236:239], v[106:109], v[66:81]
	ds_read_b128 v[232:235], v196 offset:8192
	ds_read_b128 v[236:239], v196 offset:12288
	s_waitcnt lgkmcnt(0)
	v_mfma_f32_32x32x16_bf16 v[82:97], v[232:235], v[102:105], v[82:97]
	v_mfma_f32_32x32x16_bf16 v[66:81], v[236:239], v[102:105], v[66:81]
	ds_read_b128 v[232:235], v199 offset:8192
	ds_read_b128 v[236:239], v199 offset:12288
	s_waitcnt lgkmcnt(0)
	v_mfma_f32_32x32x16_bf16 v[82:97], v[232:235], v[98:101], v[82:97]
	v_exp_f32_e32 v232, v154
	v_exp_f32_e32 v233, v155
	v_exp_f32_e32 v234, v152
	v_exp_f32_e32 v235, v153
	v_add_f32_e32 v146, v232, v146
	v_add_f32_e32 v146, v233, v146
	v_add_f32_e32 v146, v234, v146
	v_mfma_f32_32x32x16_bf16 v[66:81], v[236:239], v[98:101], v[66:81]
	v_exp_f32_e32 v236, v150
	v_exp_f32_e32 v237, v151
	v_exp_f32_e32 v238, v148
	v_exp_f32_e32 v239, v149
	v_add_f32_e32 v146, v235, v146
	v_add_f32_e32 v146, v236, v146
	v_add_f32_e32 v146, v237, v146
	v_add_f32_e32 v146, v238, v146
	v_add_f32_e32 v146, v239, v146
	v_add_f32_e32 v146, v240, v146
	v_add_f32_e32 v162, v241, v146
	v_mov_b32_e32 v163, v162
	s_nop 1
	v_permlane32_swap_b32_e32 v162, v163
	v_cvt_pk_bf16_f32 v146, v229, v231
	v_cvt_pk_bf16_f32 v147, v227, v230
	v_cvt_pk_bf16_f32 v148, v226, v228
	v_cvt_pk_bf16_f32 v149, v224, v225
	v_cvt_pk_bf16_f32 v150, v221, v223
	v_cvt_pk_bf16_f32 v151, v220, v222
	v_cvt_pk_bf16_f32 v152, v217, v219
	v_cvt_pk_bf16_f32 v153, v216, v218
	v_cvt_pk_bf16_f32 v154, v164, v165
	v_cvt_pk_bf16_f32 v155, v197, v215
	v_cvt_pk_bf16_f32 v156, v156, v157
	v_cvt_pk_bf16_f32 v157, v232, v233
	v_cvt_pk_bf16_f32 v216, v234, v235
	v_cvt_pk_bf16_f32 v217, v236, v237
	v_cvt_pk_bf16_f32 v218, v238, v239
	v_cvt_pk_bf16_f32 v219, v240, v241
	s_nop 0
	v_permlane32_swap_b32_e32 v146, v148
	v_permlane32_swap_b32_e32 v147, v149
	v_permlane32_swap_b32_e32 v150, v152
	v_permlane32_swap_b32_e32 v151, v153
	v_permlane32_swap_b32_e32 v154, v156
	v_permlane32_swap_b32_e32 v155, v157
	v_permlane32_swap_b32_e32 v216, v218
	v_permlane32_swap_b32_e32 v217, v219
	s_lshl_b32 s24, s17, 14
	v_add_u32_e32 v197, s24, v200
	ds_read_b64_tr_b16 v[228:229], v197 offset:0x2000
	ds_read_b64_tr_b16 v[230:231], v197 offset:0x2800
	ds_read_b64_tr_b16 v[232:233], v197 offset:0x3000
	ds_read_b64_tr_b16 v[234:235], v197 offset:0x3800
	s_nop 0
	v_mfma_f32_32x32x16_bf16 v[2:17], v[146:149], v[206:209], v[2:17]
	ds_read_b64_tr_b16 v[220:221], v197 offset:0x200
	ds_read_b64_tr_b16 v[222:223], v197 offset:0xa00
	v_max_f32_e32 v164, v83, v83
	v_max_f32_e32 v165, v82, v82
	v_max_f32_e32 v164, v165, v164
	v_max3_f32 v164, v164, v84, v85
	v_max3_f32 v164, v164, v86, v87
	v_mfma_f32_32x32x16_bf16 v[2:17], v[150:153], v[210:213], v[2:17]
	ds_read_b64_tr_b16 v[224:225], v197 offset:0x1200
	ds_read_b64_tr_b16 v[226:227], v197 offset:0x1a00
	v_max3_f32 v164, v164, v88, v89
	v_max3_f32 v164, v164, v90, v91
	v_max3_f32 v164, v164, v92, v93
	v_max3_f32 v164, v164, v94, v95
	v_max3_f32 v164, v164, v96, v97
	s_waitcnt lgkmcnt(6)
	v_mfma_f32_32x32x16_bf16 v[2:17], v[154:157], v[228:231], v[2:17]
	ds_read_b64_tr_b16 v[228:229], v197 offset:0x2200
	ds_read_b64_tr_b16 v[230:231], v197 offset:0x2a00
	ds_read_b64_tr_b16 v[236:237], v197 offset:0x3200
	ds_read_b64_tr_b16 v[238:239], v197 offset:0x3a00
	s_waitcnt lgkmcnt(8)
	v_mfma_f32_32x32x16_bf16 v[2:17], v[216:219], v[232:235], v[2:17]
	s_waitcnt lgkmcnt(6)
	v_mfma_f32_32x32x16_bf16 v[50:65], v[146:149], v[220:223], v[50:65]
	v_max3_f32 v164, v164, v66, v67
	v_max3_f32 v164, v164, v68, v69
	v_max3_f32 v164, v164, v70, v71
	v_max3_f32 v164, v164, v72, v73
	v_max3_f32 v164, v164, v74, v75
	v_max3_f32 v164, v164, v76, v77
	v_max3_f32 v164, v164, v78, v79
	s_waitcnt lgkmcnt(4)
	v_mfma_f32_32x32x16_bf16 v[50:65], v[150:153], v[224:227], v[50:65]
	v_max3_f32 v164, v164, v80, v81
	v_mov_b32_e32 v165, v164
	s_nop 1
	v_permlane32_swap_b32_e32 v164, v165
	ds_read_b64_tr_b16 v[220:221], v197 offset:0x400
	v_max_f32_e32 v165, v165, v165
	v_max_f32_e32 v164, v164, v164
	s_waitcnt lgkmcnt(3)
	v_mfma_f32_32x32x16_bf16 v[50:65], v[154:157], v[228:231], v[50:65]
	ds_read_b64_tr_b16 v[222:223], v197 offset:0xc00
	v_max_f32_e32 v164, v164, v165
	v_max_f32_e32 v165, v202, v202
	ds_read_b64_tr_b16 v[224:225], v197 offset:0x1400
	v_max_f32_e32 v165, v165, v164
	ds_read_b64_tr_b16 v[226:227], v197 offset:0x1c00
	v_sub_f32_e32 v215, v164, v202
	s_waitcnt lgkmcnt(4)
	v_mfma_f32_32x32x16_bf16 v[50:65], v[216:219], v[236:239], v[50:65]
	v_sub_f32_e32 v164, v202, v165
	ds_read_b64_tr_b16 v[228:229], v197 offset:0x2400
	v_mul_f32_e32 v164, 0x3dd53b94, v164
	ds_read_b64_tr_b16 v[230:231], v197 offset:0x2c00
	v_exp_f32_e32 v164, v164
	ds_read_b64_tr_b16 v[232:233], v197 offset:0x3400
	v_cmp_ge_f32_e32 vcc, s77, v215
	ds_read_b64_tr_b16 v[234:235], v197 offset:0x3c00
	s_cmp_eq_u64 vcc, exec
	s_cselect_b64 s[4:5], -1, 0
	v_cndmask_b32_e64 v164, v164, 1.0, s[4:5]
	s_waitcnt lgkmcnt(6)
	v_mfma_f32_32x32x16_bf16 v[34:49], v[146:149], v[220:223], v[34:49]
	ds_read_b64_tr_b16 v[220:221], v197 offset:0x600
	ds_read_b64_tr_b16 v[222:223], v197 offset:0xe00
	s_waitcnt lgkmcnt(6)
	v_mfma_f32_32x32x16_bf16 v[34:49], v[150:153], v[224:227], v[34:49]
	ds_read_b64_tr_b16 v[224:225], v197 offset:0x1600
	ds_read_b64_tr_b16 v[226:227], v197 offset:0x1e00
	s_waitcnt lgkmcnt(6)
	v_mfma_f32_32x32x16_bf16 v[34:49], v[154:157], v[228:231], v[34:49]
	ds_read_b64_tr_b16 v[228:229], v197 offset:0x2600
	ds_read_b64_tr_b16 v[230:231], v197 offset:0x2e00
	ds_read_b64_tr_b16 v[236:237], v197 offset:0x3600
	ds_read_b64_tr_b16 v[238:239], v197 offset:0x3e00
	s_waitcnt lgkmcnt(8)
	v_mfma_f32_32x32x16_bf16 v[34:49], v[216:219], v[232:235], v[34:49]
	s_waitcnt lgkmcnt(6)
	v_mfma_f32_32x32x16_bf16 v[18:33], v[146:149], v[220:223], v[18:33]
	v_cmp_gt_f32_e32 vcc, 1.0, v164
	s_waitcnt lgkmcnt(4)
	v_mfma_f32_32x32x16_bf16 v[18:33], v[150:153], v[224:227], v[18:33]
	s_waitcnt lgkmcnt(2)
	v_mfma_f32_32x32x16_bf16 v[18:33], v[154:157], v[228:231], v[18:33]
	s_waitcnt lgkmcnt(0)
	v_mfma_f32_32x32x16_bf16 v[18:33], v[216:219], v[236:239], v[18:33]
	s_cbranch_vccz .LBB0_547
	s_and_saveexec_b64 s[0:1], s[2:3]
	ds_write_b32 v170, v164 offset:128
	s_or_b64 exec, exec, s[0:1]
	s_waitcnt lgkmcnt(0)
	ds_read_b128 v[146:149], v158 offset:224
	ds_read_b128 v[150:153], v158 offset:192
	ds_read_b128 v[154:157], v158 offset:160
	ds_read_b128 v[216:219], v158 offset:128
	s_waitcnt lgkmcnt(0)
	v_pk_mul_f32 v[16:17], v[16:17], v[148:149]
	v_pk_mul_f32 v[12:13], v[12:13], v[152:153]
	v_pk_mul_f32 v[8:9], v[8:9], v[156:157]
	v_pk_mul_f32 v[4:5], v[4:5], v[218:219]
	v_pk_mul_f32 v[14:15], v[14:15], v[146:147]
	v_pk_mul_f32 v[10:11], v[10:11], v[150:151]
	v_pk_mul_f32 v[6:7], v[6:7], v[154:155]
	v_pk_mul_f32 v[2:3], v[2:3], v[216:217]
	v_pk_mul_f32 v[64:65], v[64:65], v[148:149]
	v_pk_mul_f32 v[60:61], v[60:61], v[152:153]
	v_pk_mul_f32 v[56:57], v[56:57], v[156:157]
	v_pk_mul_f32 v[52:53], v[52:53], v[218:219]
	v_pk_mul_f32 v[62:63], v[62:63], v[146:147]
	v_pk_mul_f32 v[58:59], v[58:59], v[150:151]
	v_pk_mul_f32 v[54:55], v[54:55], v[154:155]
	v_pk_mul_f32 v[50:51], v[50:51], v[216:217]
	v_pk_mul_f32 v[48:49], v[48:49], v[148:149]
	v_pk_mul_f32 v[44:45], v[44:45], v[152:153]
	v_pk_mul_f32 v[40:41], v[40:41], v[156:157]
	v_pk_mul_f32 v[36:37], v[36:37], v[218:219]
	v_pk_mul_f32 v[46:47], v[46:47], v[146:147]
	v_pk_mul_f32 v[42:43], v[42:43], v[150:151]
	v_pk_mul_f32 v[38:39], v[38:39], v[154:155]
	v_pk_mul_f32 v[34:35], v[34:35], v[216:217]
	v_pk_mul_f32 v[32:33], v[32:33], v[148:149]
	v_pk_mul_f32 v[28:29], v[28:29], v[152:153]
	v_pk_mul_f32 v[24:25], v[24:25], v[156:157]
	v_pk_mul_f32 v[20:21], v[20:21], v[218:219]
	v_pk_mul_f32 v[30:31], v[30:31], v[146:147]
	v_pk_mul_f32 v[26:27], v[26:27], v[150:151]
	v_pk_mul_f32 v[22:23], v[22:23], v[154:155]
	v_pk_mul_f32 v[18:19], v[18:19], v[216:217]

.LBB0_549:
	v_cndmask_b32_e64 v165, v165, v202, s[4:5]
	v_mul_f32_e32 v154, 0xbdd53b94, v165
	v_fmamk_f32 v202, v69, 0x3dd53b94, v154
	v_fmamk_f32 v215, v70, 0x3dd53b94, v154
	v_fmamk_f32 v155, v66, 0x3dd53b94, v154
	v_fmamk_f32 v156, v67, 0x3dd53b94, v154
	v_fmamk_f32 v157, v68, 0x3dd53b94, v154
	v_fmamk_f32 v216, v71, 0x3dd53b94, v154
	v_fmamk_f32 v217, v72, 0x3dd53b94, v154
	v_fmamk_f32 v218, v73, 0x3dd53b94, v154
	ds_read_b128 v[66:69], v174 offset:32768
	ds_read_b128 v[70:73], v174 offset:40960
	ds_read_b128 v[146:149], v176 offset:32768
	ds_read_b128 v[150:153], v176 offset:40960
	s_cmp_lg_u32 s98, 0
	s_cbranch_scc1 .Lmla_nopf_valu
	s_add_u32 s0, s38, s20
	s_addc_u32 s1, s39, s21
	s_add_u32 s100, s0, s42
	s_addc_u32 s101, s1, s43
	s_mov_b32 m0, s93
	s_nop 0
	global_load_lds_dwordx4 v246, s[100:101]
	v_fmamk_f32 v224, v82, 0x3dd53b94, v154
	v_fmamk_f32 v225, v83, 0x3dd53b94, v154
	v_fmamk_f32 v226, v84, 0x3dd53b94, v154
	s_add_u32 s100, s0, s46
	s_addc_u32 s101, s1, s47
	s_mov_b32 m0, s94
	s_nop 0
	global_load_lds_dwordx4 v246, s[100:101]
	v_fmamk_f32 v227, v85, 0x3dd53b94, v154
	v_fmamk_f32 v228, v86, 0x3dd53b94, v154
	v_fmamk_f32 v229, v87, 0x3dd53b94, v154
	s_add_u32 s100, s0, s44
	s_addc_u32 s101, s1, s45
	s_add_i32 s98, s89, s24
	s_mov_b32 m0, s98
	s_nop 0
	global_load_lds_dwordx4 v248, s[100:101]
	v_fmamk_f32 v230, v88, 0x3dd53b94, v154
	v_fmamk_f32 v231, v89, 0x3dd53b94, v154
	v_fmamk_f32 v234, v90, 0x3dd53b94, v154
	s_add_u32 s100, s0, s50
	s_addc_u32 s101, s1, s51
	s_add_i32 m0, s98, 0x2000
	s_nop 0
	global_load_lds_dwordx4 v248, s[100:101]
	v_fmamk_f32 v235, v91, 0x3dd53b94, v154
	v_fmamk_f32 v236, v92, 0x3dd53b94, v154
	v_fmamk_f32 v237, v93, 0x3dd53b94, v154
	s_add_u32 s0, s38, s88
	s_addc_u32 s1, s39, s87
	s_add_u32 s0, s0, s58
	s_addc_u32 s1, s1, s59
	s_mov_b32 m0, s95
	s_nop 0
	global_load_lds_dwordx4 v250, s[0:1]
	v_fmamk_f32 v238, v94, 0x3dd53b94, v154
	v_fmamk_f32 v239, v95, 0x3dd53b94, v154
	v_fmamk_f32 v240, v96, 0x3dd53b94, v154
	v_fmamk_f32 v241, v97, 0x3dd53b94, v154
.Lattn_mla_nopf:
	s_waitcnt lgkmcnt(0)
	v_mfma_f32_32x32x16_bf16 v[82:97], v[66:69], v[142:145], 0
	v_fmamk_f32 v232, v79, 0x3dd53b94, v154
	v_fmamk_f32 v233, v80, 0x3dd53b94, v154
	v_fmamk_f32 v219, v74, 0x3dd53b94, v154
	v_fmamk_f32 v220, v75, 0x3dd53b94, v154
	v_fmamk_f32 v221, v76, 0x3dd53b94, v154
	v_fmamk_f32 v222, v77, 0x3dd53b94, v154
	v_fmamk_f32 v223, v78, 0x3dd53b94, v154
	v_fmac_f32_e32 v154, 0x3dd53b94, v81
	v_mfma_f32_32x32x16_bf16 v[66:81], v[70:73], v[142:145], 0
	v_exp_f32_e32 v224, v224
	v_exp_f32_e32 v225, v225
	v_exp_f32_e32 v226, v226
	v_add_f32_e32 v245, 0, v224
	v_add_f32_e32 v245, v225, v245
	v_add_f32_e32 v245, v226, v245
	v_mfma_f32_32x32x16_bf16 v[82:97], v[146:149], v[138:141], v[82:97]
	v_exp_f32_e32 v227, v227
	v_exp_f32_e32 v228, v228
	v_add_f32_e32 v245, v227, v245
	v_add_f32_e32 v245, v228, v245
	v_mfma_f32_32x32x16_bf16 v[66:81], v[150:153], v[138:141], v[66:81]
	ds_read_b128 v[146:149], v178 offset:32768
	ds_read_b128 v[150:153], v178 offset:40960
	v_exp_f32_e32 v229, v229
	v_exp_f32_e32 v230, v230
	v_add_f32_e32 v245, v229, v245
	v_add_f32_e32 v245, v230, v245
	s_waitcnt lgkmcnt(0)
	v_mfma_f32_32x32x16_bf16 v[82:97], v[146:149], v[134:137], v[82:97]
	v_mfma_f32_32x32x16_bf16 v[66:81], v[150:153], v[134:137], v[66:81]
	ds_read_b128 v[146:149], v180 offset:32768
	ds_read_b128 v[150:153], v180 offset:40960
	v_exp_f32_e32 v231, v231
	v_exp_f32_e32 v234, v234
	v_exp_f32_e32 v235, v235
	v_add_f32_e32 v245, v231, v245
	v_add_f32_e32 v245, v234, v245
	v_add_f32_e32 v245, v235, v245
	s_waitcnt lgkmcnt(0)
	v_mfma_f32_32x32x16_bf16 v[82:97], v[146:149], v[130:133], v[82:97]
	v_mfma_f32_32x32x16_bf16 v[66:81], v[150:153], v[130:133], v[66:81]
	ds_read_b128 v[146:149], v182 offset:32768
	ds_read_b128 v[150:153], v182 offset:40960
	v_exp_f32_e32 v236, v236
	v_exp_f32_e32 v237, v237
	v_exp_f32_e32 v238, v238
	v_add_f32_e32 v245, v236, v245
	v_add_f32_e32 v245, v237, v245
	v_add_f32_e32 v245, v238, v245
	s_waitcnt lgkmcnt(0)
	v_mfma_f32_32x32x16_bf16 v[82:97], v[146:149], v[126:129], v[82:97]
	v_mfma_f32_32x32x16_bf16 v[66:81], v[150:153], v[126:129], v[66:81]
	ds_read_b128 v[146:149], v186 offset:32768
	ds_read_b128 v[150:153], v186 offset:40960
	v_exp_f32_e32 v239, v239
	v_exp_f32_e32 v240, v240
	v_exp_f32_e32 v241, v241
	v_add_f32_e32 v245, v239, v245
	v_add_f32_e32 v245, v240, v245
	v_add_f32_e32 v245, v241, v245
	s_waitcnt lgkmcnt(0)
	v_mfma_f32_32x32x16_bf16 v[82:97], v[146:149], v[122:125], v[82:97]
	v_mfma_f32_32x32x16_bf16 v[66:81], v[150:153], v[122:125], v[66:81]
	ds_read_b128 v[146:149], v188 offset:32768
	ds_read_b128 v[150:153], v188 offset:40960
	v_exp_f32_e32 v155, v155
	v_exp_f32_e32 v156, v156
	v_exp_f32_e32 v157, v157
	v_add_f32_e32 v245, v155, v245
	v_add_f32_e32 v245, v156, v245
	v_add_f32_e32 v245, v157, v245
	s_waitcnt lgkmcnt(0)
	v_mfma_f32_32x32x16_bf16 v[82:97], v[146:149], v[118:121], v[82:97]
	v_mfma_f32_32x32x16_bf16 v[66:81], v[150:153], v[118:121], v[66:81]
	ds_read_b128 v[146:149], v190 offset:32768
	ds_read_b128 v[150:153], v190 offset:40960
	v_exp_f32_e32 v202, v202
	v_exp_f32_e32 v215, v215
	v_exp_f32_e32 v216, v216
	v_add_f32_e32 v245, v202, v245
	v_add_f32_e32 v245, v215, v245
	v_add_f32_e32 v245, v216, v245
	s_waitcnt lgkmcnt(0)
	v_mfma_f32_32x32x16_bf16 v[82:97], v[146:149], v[114:117], v[82:97]
	v_mfma_f32_32x32x16_bf16 v[66:81], v[150:153], v[114:117], v[66:81]
	ds_read_b128 v[146:149], v192
	ds_read_b128 v[150:153], v192 offset:4096
	v_exp_f32_e32 v217, v217
	v_exp_f32_e32 v218, v218
	v_exp_f32_e32 v219, v219
	v_add_f32_e32 v245, v217, v245
	v_add_f32_e32 v245, v218, v245
	v_add_f32_e32 v245, v219, v245
	s_waitcnt lgkmcnt(0)
	v_mfma_f32_32x32x16_bf16 v[82:97], v[146:149], v[110:113], v[82:97]
	v_mfma_f32_32x32x16_bf16 v[66:81], v[150:153], v[110:113], v[66:81]
	ds_read_b128 v[146:149], v194
	ds_read_b128 v[150:153], v194 offset:4096
	v_exp_f32_e32 v220, v220
	v_exp_f32_e32 v221, v221
	v_exp_f32_e32 v222, v222
	v_add_f32_e32 v245, v220, v245
	v_add_f32_e32 v245, v221, v245
	v_add_f32_e32 v245, v222, v245
	s_waitcnt lgkmcnt(0)
	v_mfma_f32_32x32x16_bf16 v[82:97], v[146:149], v[106:109], v[82:97]
	v_mfma_f32_32x32x16_bf16 v[66:81], v[150:153], v[106:109], v[66:81]
	ds_read_b128 v[146:149], v196
	ds_read_b128 v[150:153], v196 offset:4096
	v_exp_f32_e32 v223, v223
	v_exp_f32_e32 v242, v232
	v_exp_f32_e32 v243, v233
	v_add_f32_e32 v245, v223, v245
	v_add_f32_e32 v245, v242, v245
	v_add_f32_e32 v245, v243, v245
	s_waitcnt lgkmcnt(0)
	v_mfma_f32_32x32x16_bf16 v[82:97], v[146:149], v[102:105], v[82:97]
	v_mfma_f32_32x32x16_bf16 v[66:81], v[150:153], v[102:105], v[66:81]
	ds_read_b128 v[146:149], v199
	ds_read_b128 v[150:153], v199 offset:4096
	v_lshl_add_u32 v214, s23, 14, v200
	ds_read_b64_tr_b16 v[206:207], v214 offset:0
	ds_read_b64_tr_b16 v[208:209], v214 offset:0x800
	ds_read_b64_tr_b16 v[210:211], v214 offset:0x1000
	ds_read_b64_tr_b16 v[212:213], v214 offset:0x1800
	v_exp_f32_e32 v244, v154
	s_waitcnt lgkmcnt(4)
	v_mfma_f32_32x32x16_bf16 v[82:97], v[146:149], v[98:101], v[82:97]
	v_mfma_f32_32x32x16_bf16 v[66:81], v[150:153], v[98:101], v[66:81]
	v_add_f32_e32 v232, v244, v245
	v_mov_b32_e32 v233, v232
	s_nop 1
	v_permlane32_swap_b32_e32 v232, v233
	v_cvt_pk_bf16_f32 v146, v224, v225
	v_cvt_pk_bf16_f32 v147, v226, v227
	v_cvt_pk_bf16_f32 v148, v228, v229
	v_cvt_pk_bf16_f32 v149, v230, v231
	v_cvt_pk_bf16_f32 v150, v234, v235
	v_cvt_pk_bf16_f32 v151, v236, v237
	v_cvt_pk_bf16_f32 v152, v238, v239
	v_cvt_pk_bf16_f32 v153, v240, v241
	v_cvt_pk_bf16_f32 v154, v155, v156
	v_cvt_pk_bf16_f32 v155, v157, v202
	v_cvt_pk_bf16_f32 v156, v215, v216
	v_cvt_pk_bf16_f32 v157, v217, v218
	v_cvt_pk_bf16_f32 v216, v219, v220
	v_cvt_pk_bf16_f32 v217, v221, v222
	v_cvt_pk_bf16_f32 v218, v223, v242
	v_cvt_pk_bf16_f32 v219, v243, v244
	s_nop 0
	v_permlane32_swap_b32_e32 v146, v148
	v_permlane32_swap_b32_e32 v147, v149
	v_permlane32_swap_b32_e32 v150, v152
	v_permlane32_swap_b32_e32 v151, v153
	v_permlane32_swap_b32_e32 v154, v156
	v_permlane32_swap_b32_e32 v155, v157
	v_permlane32_swap_b32_e32 v216, v218
	v_permlane32_swap_b32_e32 v217, v219
	ds_read_b64_tr_b16 v[228:229], v214 offset:0x2000
	ds_read_b64_tr_b16 v[230:231], v214 offset:0x2800
	ds_read_b64_tr_b16 v[234:235], v214 offset:0x3000
	ds_read_b64_tr_b16 v[236:237], v214 offset:0x3800
	s_nop 0
	s_waitcnt lgkmcnt(6)
	v_mfma_f32_32x32x16_bf16 v[2:17], v[146:149], v[206:209], v[2:17]
	ds_read_b64_tr_b16 v[220:221], v214 offset:0x200
	ds_read_b64_tr_b16 v[222:223], v214 offset:0xa00
	v_max_f32_e32 v202, v83, v83
	v_max_f32_e32 v215, v82, v82
	v_max_f32_e32 v202, v215, v202
	v_max3_f32 v202, v202, v84, v85
	v_max3_f32 v202, v202, v86, v87
	s_waitcnt lgkmcnt(6)
	v_mfma_f32_32x32x16_bf16 v[2:17], v[150:153], v[210:213], v[2:17]
	ds_read_b64_tr_b16 v[224:225], v214 offset:0x1200
	ds_read_b64_tr_b16 v[226:227], v214 offset:0x1a00
	v_max3_f32 v202, v202, v88, v89
	v_max3_f32 v202, v202, v90, v91
	v_max3_f32 v202, v202, v92, v93
	v_max3_f32 v202, v202, v94, v95
	v_max3_f32 v202, v202, v96, v97
	s_waitcnt lgkmcnt(6)
	v_mfma_f32_32x32x16_bf16 v[2:17], v[154:157], v[228:231], v[2:17]
	ds_read_b64_tr_b16 v[228:229], v214 offset:0x2200
	ds_read_b64_tr_b16 v[230:231], v214 offset:0x2a00
	ds_read_b64_tr_b16 v[238:239], v214 offset:0x3200
	ds_read_b64_tr_b16 v[240:241], v214 offset:0x3a00
	s_waitcnt lgkmcnt(8)
	v_mfma_f32_32x32x16_bf16 v[2:17], v[216:219], v[234:237], v[2:17]
	s_waitcnt lgkmcnt(6)
	v_mfma_f32_32x32x16_bf16 v[50:65], v[146:149], v[220:223], v[50:65]
	v_max3_f32 v202, v202, v66, v67
	v_max3_f32 v202, v202, v68, v69
	v_max3_f32 v202, v202, v70, v71
	v_max3_f32 v202, v202, v72, v73
	v_max3_f32 v202, v202, v74, v75
	v_max3_f32 v202, v202, v76, v77
	v_max3_f32 v202, v202, v78, v79
	s_waitcnt lgkmcnt(4)
	v_mfma_f32_32x32x16_bf16 v[50:65], v[150:153], v[224:227], v[50:65]
	v_max3_f32 v202, v202, v80, v81
	v_mov_b32_e32 v215, v202
	s_nop 1
	v_permlane32_swap_b32_e32 v202, v215
	v_max_f32_e32 v215, v215, v215
	v_max_f32_e32 v202, v202, v202
	v_max_f32_e32 v202, v202, v215
	v_max_f32_e32 v220, v165, v165
	v_sub_f32_e32 v215, v202, v165
	v_max_f32_e32 v202, v220, v202
	v_sub_f32_e32 v220, v165, v202
	v_mul_f32_e32 v220, 0x3dd53b94, v220
	s_waitcnt lgkmcnt(2)
	v_mfma_f32_32x32x16_bf16 v[50:65], v[154:157], v[228:231], v[50:65]
	v_exp_f32_e32 v220, v220
	v_cmp_ge_f32_e32 vcc, s77, v215
	s_cmp_eq_u64 vcc, exec
	s_cselect_b64 s[4:5], -1, 0
	v_cndmask_b32_e64 v215, v220, 1.0, s[4:5]
	ds_read_b64_tr_b16 v[220:221], v214 offset:0x400
	ds_read_b64_tr_b16 v[222:223], v214 offset:0xc00
	ds_read_b64_tr_b16 v[224:225], v214 offset:0x1400
	s_waitcnt lgkmcnt(3)
	v_mfma_f32_32x32x16_bf16 v[50:65], v[216:219], v[238:241], v[50:65]
	ds_read_b64_tr_b16 v[226:227], v214 offset:0x1c00
	ds_read_b64_tr_b16 v[228:229], v214 offset:0x2400
	ds_read_b64_tr_b16 v[230:231], v214 offset:0x2c00
	ds_read_b64_tr_b16 v[234:235], v214 offset:0x3400
	ds_read_b64_tr_b16 v[236:237], v214 offset:0x3c00
	s_waitcnt lgkmcnt(6)
	v_mfma_f32_32x32x16_bf16 v[34:49], v[146:149], v[220:223], v[34:49]
	ds_read_b64_tr_b16 v[220:221], v214 offset:0x600
	ds_read_b64_tr_b16 v[222:223], v214 offset:0xe00
	s_waitcnt lgkmcnt(6)
	v_mfma_f32_32x32x16_bf16 v[34:49], v[150:153], v[224:227], v[34:49]
	ds_read_b64_tr_b16 v[224:225], v214 offset:0x1600
	ds_read_b64_tr_b16 v[226:227], v214 offset:0x1e00
	s_waitcnt lgkmcnt(6)
	v_mfma_f32_32x32x16_bf16 v[34:49], v[154:157], v[228:231], v[34:49]
	ds_read_b64_tr_b16 v[228:229], v214 offset:0x2600
	ds_read_b64_tr_b16 v[230:231], v214 offset:0x2e00
	ds_read_b64_tr_b16 v[238:239], v214 offset:0x3600
	ds_read_b64_tr_b16 v[240:241], v214 offset:0x3e00
	s_waitcnt lgkmcnt(8)
	v_mfma_f32_32x32x16_bf16 v[34:49], v[216:219], v[234:237], v[34:49]
	s_waitcnt lgkmcnt(6)
	v_mfma_f32_32x32x16_bf16 v[18:33], v[146:149], v[220:223], v[18:33]
	v_cmp_gt_f32_e32 vcc, 1.0, v215
	s_waitcnt lgkmcnt(4)
	v_mfma_f32_32x32x16_bf16 v[18:33], v[150:153], v[224:227], v[18:33]
	s_waitcnt lgkmcnt(2)
	v_mfma_f32_32x32x16_bf16 v[18:33], v[154:157], v[228:231], v[18:33]
	s_waitcnt lgkmcnt(0)
	v_mfma_f32_32x32x16_bf16 v[18:33], v[216:219], v[238:241], v[18:33]
	s_cbranch_vccz .LBB0_553
	s_and_saveexec_b64 s[0:1], s[2:3]
	ds_write_b32 v170, v215 offset:128
	s_or_b64 exec, exec, s[0:1]
	s_waitcnt lgkmcnt(0)
	ds_read_b128 v[146:149], v158 offset:224
	ds_read_b128 v[150:153], v158 offset:192
	ds_read_b128 v[154:157], v158 offset:160
	ds_read_b128 v[216:219], v158 offset:128
	s_waitcnt lgkmcnt(0)
	v_pk_mul_f32 v[16:17], v[16:17], v[148:149]
	v_pk_mul_f32 v[12:13], v[12:13], v[152:153]
	v_pk_mul_f32 v[8:9], v[8:9], v[156:157]
	v_pk_mul_f32 v[4:5], v[4:5], v[218:219]
	v_pk_mul_f32 v[14:15], v[14:15], v[146:147]
	v_pk_mul_f32 v[10:11], v[10:11], v[150:151]
	v_pk_mul_f32 v[6:7], v[6:7], v[154:155]
	v_pk_mul_f32 v[2:3], v[2:3], v[216:217]
	v_pk_mul_f32 v[64:65], v[64:65], v[148:149]
	v_pk_mul_f32 v[60:61], v[60:61], v[152:153]
	v_pk_mul_f32 v[56:57], v[56:57], v[156:157]
	v_pk_mul_f32 v[52:53], v[52:53], v[218:219]
	v_pk_mul_f32 v[62:63], v[62:63], v[146:147]
	v_pk_mul_f32 v[58:59], v[58:59], v[150:151]
	v_pk_mul_f32 v[54:55], v[54:55], v[154:155]
	v_pk_mul_f32 v[50:51], v[50:51], v[216:217]
	v_pk_mul_f32 v[48:49], v[48:49], v[148:149]
	v_pk_mul_f32 v[44:45], v[44:45], v[152:153]
	v_pk_mul_f32 v[40:41], v[40:41], v[156:157]
	v_pk_mul_f32 v[36:37], v[36:37], v[218:219]
	v_pk_mul_f32 v[46:47], v[46:47], v[146:147]
	v_pk_mul_f32 v[42:43], v[42:43], v[150:151]
	v_pk_mul_f32 v[38:39], v[38:39], v[154:155]
	v_pk_mul_f32 v[34:35], v[34:35], v[216:217]
	v_pk_mul_f32 v[32:33], v[32:33], v[148:149]
	v_pk_mul_f32 v[28:29], v[28:29], v[152:153]
	v_pk_mul_f32 v[24:25], v[24:25], v[156:157]
	v_pk_mul_f32 v[20:21], v[20:21], v[218:219]
	v_pk_mul_f32 v[30:31], v[30:31], v[146:147]
	v_pk_mul_f32 v[26:27], v[26:27], v[150:151]
	v_pk_mul_f32 v[22:23], v[22:23], v[154:155]
	v_pk_mul_f32 v[18:19], v[18:19], v[216:217]
